# attention unit top: no store drain before the barrier; static unit stride = gridDim/8
# baseline (speedup 1.0000x reference)
.LBB0_396:
	s_barrier
	v_readlane_b32 s3, v254, 20
	v_readlane_b32 s2, v254, 4
	s_add_i32 s0, s3, 1
	s_lshr_b32 s2, s2, 3
	v_writelane_b32 v254, s0, 20
	s_lshr_b32 s0, s82, 3
	s_mul_i32 s3, s3, s0
	s_add_i32 s3, s3, s2
	v_mov_b32_e32 v0, s3
	s_movk_i32 s0, 0x7f
	s_waitcnt lgkmcnt(0)
	v_cmp_lt_i32_e32 vcc, s0, v0
	s_mov_b64 s[0:1], -1
	s_cbranch_vccnz .LBB0_395
	v_mov_b32_e32 v96, v193
	s_add_i32 s0, s3, s69
	s_bfe_u32 s2, s3, 0x10005
	v_readfirstlane_b32 s1, v96
	s_ashr_i32 s4, s0, 6
	s_and_b32 s72, s3, 31
	s_bfe_u32 s0, s1, 0x20006
	s_lshl_b32 s3, s2, 2
	s_add_i32 s0, s0, s3
	v_bfe_u32 v97, v96, 5, 1
	s_bfe_u32 s7, s1, 0x10008
	s_lshl_b32 s36, s0, 6
	s_lshl_b32 s1, s72, 7
	s_lshl_b32 s6, s7, 6
	s_ashr_i32 s37, s36, 31
	v_lshlrev_b32_e32 v40, 3, v97
	s_or_b32 s70, s6, s1
	s_lshl_b32 s71, s4, 12
	s_lshl_b64 s[36:37], s[36:37], 1
	v_cvt_f32_ubyte0_e32 v9, v40
	v_and_b32_e32 v222, 31, v96
	s_add_u32 s52, s28, s36
	v_cmp_lt_i32_e32 vcc, v208, v209
	v_mul_f32_e32 v10, 0xbf549a78, v9
	v_or_b32_e32 v80, s70, v222
	s_addc_u32 s53, s29, s37
	v_lshlrev_b32_e32 v198, 4, v97
	v_cndmask_b32_e32 v0, v207, v208, vcc
	v_cmp_gt_f32_e32 vcc, s30, v10
	v_lshl_add_u64 v[56:57], s[52:53], 0, v[198:199]
	v_lshlrev_b32_e32 v221, 2, v0
	v_or_b32_e32 v0, s71, v80
	v_cndmask_b32_e32 v10, 0, v213, vcc
	v_mad_i64_i32 v[0:1], s[52:53], v0, s25, v[56:57]
	v_and_b32_e32 v8, 32, v96
	v_fmac_f32_e32 v10, 0xbf549a78, v9
	s_lshl_b32 s98, s4, 8
	s_add_i32 s98, s98, 0x10000
	v_lshrrev_b32_e32 v238, 2, v193
	v_add_u32_e32 v238, s98, v238
	v_mov_b64_e32 v[240:241], s[28:29]
	v_mad_u64_u32 v[240:241], s[100:101], v238, s25, v[240:241]
	s_lshl_b32 s98, s2, 7
	s_mov_b32 s99, 0
	v_lshl_add_u64 v[240:241], v[240:241], 0, s[98:99]
	v_bfe_u32 v242, v193, 1, 1
	v_mov_b32_e32 v243, 0
	v_lshlrev_b32_e32 v242, 6, v242
	v_lshl_add_u64 v[244:245], v[240:241], 0, v[242:243]
	v_and_b32_e32 v242, 1, v193
	v_lshlrev_b32_e32 v242, 4, v242
	v_lshl_add_u64 v[244:245], v[244:245], 0, v[242:243]
	v_and_b32_e32 v242, 3, v193
	v_lshlrev_b32_e32 v242, 5, v242
	v_lshl_add_u64 v[246:247], v[240:241], 0, v[242:243]
	global_load_dwordx4 v[176:179], v[244:245], off offset:1024
	global_load_dwordx4 v[180:183], v[244:245], off offset:1056
	global_load_dwordx4 v[184:187], v[246:247], off offset:1296
	global_load_dwordx4 v[188:191], v[246:247], off offset:1280
	global_load_dwordx4 v[24:27], v[0:1], off
	global_load_dwordx4 v[28:31], v[0:1], off offset:32
	global_load_dwordx4 v[88:91], v[0:1], off offset:64
	global_load_dwordx4 v[92:95], v[0:1], off offset:96
	global_load_dwordx4 v[16:19], v8, s[14:15]
	global_load_dwordx4 v[20:23], v8, s[14:15] offset:16
	global_load_dwordx4 v[4:7], v8, s[14:15] offset:64
	s_nop 0
	global_load_dwordx4 v[0:3], v8, s[14:15] offset:80
	global_load_dwordx4 v[100:103], v8, s[14:15] offset:128
	global_load_dwordx4 v[52:55], v8, s[14:15] offset:144
	v_exp_f32_e32 v32, v10
	global_load_dwordx4 v[12:15], v8, s[14:15] offset:192
	s_nop 0
	global_load_dwordx4 v[8:11], v8, s[14:15] offset:208
	v_cndmask_b32_e32 v33, 0, v214, vcc
	s_lshr_b32 s1, s70, 6
	v_ldexp_f32 v81, v32, v33
	v_or_b32_e32 v33, 1, v40
	v_cvt_f32_ubyte0_e32 v33, v33
	v_mul_f32_e32 v34, 0xbf549a78, v33
	v_cmp_gt_f32_e32 vcc, s30, v34
	v_cvt_f32_ubyte0_e32 v41, s1
	v_mul_f32_e32 v32, v81, v41
	v_cndmask_b32_e32 v34, 0, v213, vcc
	v_fmac_f32_e32 v34, 0xbf549a78, v33
	v_cvt_f32_ubyte0_e32 v50, v222
	v_mul_f32_e32 v32, 0.15915494, v32
	v_exp_f32_e32 v33, v34
	v_sin_f32_e32 v42, v32
	v_cos_f32_e32 v43, v32
	v_mul_f32_e32 v32, v81, v50
	v_mul_f32_e32 v32, 0.15915494, v32
	v_sin_f32_e32 v62, v32
	v_cos_f32_e32 v63, v32
	v_cndmask_b32_e32 v32, 0, v214, vcc
	v_ldexp_f32 v82, v33, v32
	v_or_b32_e32 v33, 2, v40
	v_cvt_f32_ubyte0_e32 v33, v33
	v_mul_f32_e32 v34, 0xbf549a78, v33
	v_cmp_gt_f32_e32 vcc, s30, v34
	v_mul_f32_e32 v32, v82, v41
	v_mul_f32_e32 v32, 0.15915494, v32
	v_cndmask_b32_e32 v34, 0, v213, vcc
	v_fmac_f32_e32 v34, 0xbf549a78, v33
	v_exp_f32_e32 v33, v34
	v_sin_f32_e32 v45, v32
	v_cos_f32_e32 v44, v32
	v_mul_f32_e32 v32, v82, v50
	v_mul_f32_e32 v32, 0.15915494, v32
	v_sin_f32_e32 v65, v32
	v_cos_f32_e32 v64, v32
	v_cndmask_b32_e32 v32, 0, v214, vcc
	v_ldexp_f32 v83, v33, v32
	v_or_b32_e32 v33, 3, v40
	v_cvt_f32_ubyte0_e32 v33, v33
	v_mul_f32_e32 v34, 0xbf549a78, v33
	v_mul_f32_e32 v32, v83, v41
	v_cmp_gt_f32_e32 vcc, s30, v34
	v_mul_f32_e32 v32, 0.15915494, v32
	v_or_b32_e32 v35, 4, v40
	v_cndmask_b32_e32 v34, 0, v213, vcc
	v_sin_f32_e32 v46, v32
	v_cos_f32_e32 v47, v32
	v_mul_f32_e32 v32, v83, v50
	v_fmac_f32_e32 v34, 0xbf549a78, v33
	v_cvt_f32_ubyte0_e32 v35, v35
	v_mul_f32_e32 v32, 0.15915494, v32
	v_exp_f32_e32 v33, v34
	v_mul_f32_e32 v36, 0xbf549a78, v35
	v_sin_f32_e32 v70, v32
	v_cos_f32_e32 v71, v32
	v_cndmask_b32_e32 v32, 0, v214, vcc
	v_cmp_gt_f32_e32 vcc, s30, v36
	v_ldexp_f32 v84, v33, v32
	v_or_b32_e32 v37, 5, v40
	v_cndmask_b32_e32 v36, 0, v213, vcc
	v_fmac_f32_e32 v36, 0xbf549a78, v35
	v_exp_f32_e32 v35, v36
	v_mul_f32_e32 v34, v84, v50
	v_cvt_f32_ubyte0_e32 v37, v37
	v_mul_f32_e32 v34, 0.15915494, v34
	v_mul_f32_e32 v38, 0xbf549a78, v37
	v_sin_f32_e32 v73, v34
	v_cos_f32_e32 v72, v34
	v_cndmask_b32_e32 v34, 0, v214, vcc
	v_cmp_gt_f32_e32 vcc, s30, v38
	v_ldexp_f32 v85, v35, v34
	v_or_b32_e32 v39, 6, v40
	v_cndmask_b32_e32 v38, 0, v213, vcc
	v_mul_f32_e32 v36, v85, v50
	v_fmac_f32_e32 v38, 0xbf549a78, v37
	v_cvt_f32_ubyte0_e32 v39, v39
	v_mul_f32_e32 v36, 0.15915494, v36
	v_exp_f32_e32 v37, v38
	v_mul_f32_e32 v48, 0xbf549a78, v39
	v_sin_f32_e32 v74, v36
	v_cos_f32_e32 v75, v36
	v_cndmask_b32_e32 v36, 0, v214, vcc
	v_cmp_gt_f32_e32 vcc, s30, v48
	v_ldexp_f32 v86, v37, v36
	v_mul_f32_e32 v38, v86, v50
	v_cndmask_b32_e32 v48, 0, v213, vcc
	v_fmac_f32_e32 v48, 0xbf549a78, v39
	v_exp_f32_e32 v39, v48
	v_mul_f32_e32 v38, 0.15915494, v38
	v_sin_f32_e32 v77, v38
	v_cos_f32_e32 v76, v38
	v_cndmask_b32_e32 v38, 0, v214, vcc
	v_ldexp_f32 v87, v39, v38
	v_mul_f32_e32 v48, v87, v50
	v_or_b32_e32 v40, 7, v40
	v_mul_f32_e32 v48, 0.15915494, v48
	v_cvt_f32_ubyte0_e32 v40, v40
	v_sin_f32_e32 v66, v48
	v_cos_f32_e32 v67, v48
	v_mul_f32_e32 v48, 0xbf549a78, v40
	v_cmp_gt_f32_e32 vcc, s30, v48
	s_waitcnt vmcnt(0)
	v_mov_b32_e32 v49, v10
	v_lshlrev_b32_e32 v60, 16, v91
	v_cndmask_b32_e32 v48, 0, v213, vcc
	v_fmac_f32_e32 v48, 0xbf549a78, v40
	v_exp_f32_e32 v40, v48
	v_cndmask_b32_e32 v10, 0, v214, vcc
	v_and_b32_e32 v104, 0xffff0000, v91
	v_mul_f32_e32 v32, v84, v41
	v_ldexp_f32 v99, v40, v10
	v_mul_f32_e32 v10, v99, v41
	v_mul_f32_e32 v10, 0.15915494, v10
	v_mul_f32_e32 v34, v85, v41
	v_mul_f32_e32 v36, v86, v41
	v_mul_f32_e32 v38, v87, v41
	v_lshlrev_b32_e32 v61, 16, v95
	v_sin_f32_e32 v41, v10
	v_cos_f32_e32 v40, v10
	v_mul_f32_e32 v10, v99, v50
	v_and_b32_e32 v105, 0xffff0000, v95
	v_mov_b32_e32 v50, v104
	v_mov_b32_e32 v51, v60
	v_pk_mul_f32 v[106:107], v[50:51], v[50:51]
	v_mov_b32_e32 v50, v105
	v_mov_b32_e32 v51, v61
	v_pk_mul_f32 v[108:109], v[50:51], v[50:51]
	v_mov_b32_e32 v51, v8
	v_mov_b32_e32 v8, v53
	v_lshlrev_b32_e32 v112, 16, v89
	v_mov_b32_e32 v53, v14
	v_and_b32_e32 v114, 0xffff0000, v89
	v_mov_b32_e32 v14, v103
	v_lshlrev_b32_e32 v103, 16, v92
	v_and_b32_e32 v89, 0xffff0000, v92
	v_lshlrev_b32_e32 v140, 16, v25
	v_and_b32_e32 v144, 0xffff0000, v25
	v_lshlrev_b32_e32 v149, 16, v28
	v_lshlrev_b32_e32 v148, 16, v24
	v_and_b32_e32 v25, 0xffff0000, v28
	v_and_b32_e32 v24, 0xffff0000, v24
	v_mov_b32_e32 v58, v89
	v_mov_b32_e32 v59, v103
	v_lshlrev_b32_e32 v141, 16, v29
	v_and_b32_e32 v145, 0xffff0000, v29
	v_pk_mul_f32 v[150:151], v[148:149], v[148:149]
	v_pk_mul_f32 v[28:29], v[24:25], v[24:25]
	v_lshlrev_b32_e32 v113, 16, v93
	v_and_b32_e32 v115, 0xffff0000, v93
	v_pk_mul_f32 v[92:93], v[58:59], v[58:59]
	v_mov_b32_e32 v58, v22
	v_mov_b32_e32 v22, v20
	v_pk_mul_f32 v[142:143], v[140:141], v[140:141]
	v_add_f32_e32 v20, v150, v28
	v_lshlrev_b32_e32 v137, 16, v30
	v_lshlrev_b32_e32 v136, 16, v26
	v_pk_mul_f32 v[146:147], v[144:145], v[144:145]
	v_add_f32_e32 v20, v142, v20
	v_lshlrev_b32_e32 v128, 16, v27
	v_and_b32_e32 v132, 0xffff0000, v27
	v_pk_mul_f32 v[138:139], v[136:137], v[136:137]
	v_and_b32_e32 v27, 0xffff0000, v30
	v_and_b32_e32 v26, 0xffff0000, v26
	v_add_f32_e32 v20, v146, v20
	v_lshlrev_b32_e32 v129, 16, v31
	v_and_b32_e32 v133, 0xffff0000, v31
	v_pk_mul_f32 v[30:31], v[26:27], v[26:27]
	v_add_f32_e32 v20, v138, v20
	v_pk_mul_f32 v[130:131], v[128:129], v[128:129]
	v_add_f32_e32 v20, v30, v20
	v_pk_mul_f32 v[134:135], v[132:133], v[132:133]
	v_add_f32_e32 v20, v130, v20
	v_add_f32_e32 v20, v134, v20
	v_add_f32_e32 v20, v151, v20
	v_add_f32_e32 v20, v29, v20
	v_add_f32_e32 v20, v143, v20
	v_add_f32_e32 v20, v147, v20
	v_add_f32_e32 v20, v139, v20
	v_add_f32_e32 v20, v31, v20
	v_add_f32_e32 v20, v131, v20
	v_mov_b32_e32 v50, v52
	v_mov_b32_e32 v52, v102
	v_lshlrev_b32_e32 v102, 16, v88
	v_add_f32_e32 v20, v135, v20
	v_and_b32_e32 v88, 0xffff0000, v88
	v_fmac_f32_e32 v20, v102, v102
	v_fmac_f32_e32 v20, v88, v88
	v_fmac_f32_e32 v20, v112, v112
	v_lshlrev_b32_e32 v110, 16, v90
	v_fmac_f32_e32 v20, v114, v114
	v_and_b32_e32 v90, 0xffff0000, v90
	v_fmac_f32_e32 v20, v110, v110
	v_fmac_f32_e32 v20, v90, v90
	v_mul_f32_e32 v10, 0.15915494, v10
	v_lshlrev_b32_e32 v111, 16, v94
	v_and_b32_e32 v91, 0xffff0000, v94
	v_add_f32_e32 v20, v107, v20
	v_mov_b32_e32 v48, v54
	v_sin_f32_e32 v69, v10
	v_cos_f32_e32 v68, v10
	v_mov_b32_e32 v10, v55
	v_mov_b32_e32 v54, v91
	v_mov_b32_e32 v55, v111
	v_add_f32_e32 v20, v106, v20
	v_pk_mul_f32 v[94:95], v[54:55], v[54:55]
	v_mov_b32_e32 v54, v115
	v_mov_b32_e32 v55, v113
	v_add_f32_e32 v20, v93, v20
	v_pk_mul_f32 v[116:117], v[54:55], v[54:55]
	v_add_f32_e32 v20, v92, v20
	v_add_f32_e32 v20, v117, v20
	v_add_f32_e32 v20, v116, v20
	v_add_f32_e32 v20, v95, v20
	v_add_f32_e32 v20, v94, v20
	v_add_f32_e32 v20, v109, v20
	v_add_f32_e32 v20, v108, v20
	ds_bpermute_b32 v30, v221, v20
	v_mov_b32_e32 v29, v6
	v_mov_b32_e32 v28, v18
	v_mov_b32_e32 v31, v4
	v_mov_b32_e32 v54, v100
	s_waitcnt lgkmcnt(0)
	v_add_f32_e32 v6, v20, v30
	v_fmamk_f32 v6, v6, 0x3c800000, v211
	v_mul_f32_e32 v18, 0x4b800000, v6
	v_cmp_gt_f32_e32 vcc, s33, v6
	v_mov_b32_e32 v55, v12
	v_mov_b32_e32 v30, v16
	v_cndmask_b32_e32 v6, v6, v18, vcc
	v_rsq_f32_e32 v18, v6
	v_mov_b32_e32 v12, v101
	v_mov_b32_e32 v59, v2
	v_mov_b32_e32 v2, v23
	v_mul_f32_e32 v4, 0x45800000, v18
	v_cndmask_b32_e32 v16, v18, v4, vcc
	v_pk_mul_f32 v[116:117], v[54:55], v[16:17] op_sel_hi:[1,0]
	v_mov_b32_e32 v23, v0
	v_pk_mul_f32 v[102:103], v[116:117], v[102:103]
	v_pk_mul_f32 v[116:117], v[12:13], v[16:17] op_sel_hi:[1,0]
	v_mov_b32_e32 v0, v21
	v_pk_mul_f32 v[88:89], v[116:117], v[88:89]
	v_pk_mul_f32 v[116:117], v[52:53], v[16:17] op_sel_hi:[1,0]
	v_mov_b32_e32 v4, v17
	v_pk_mul_f32 v[112:113], v[116:117], v[112:113]
	v_pk_mul_f32 v[116:117], v[14:15], v[16:17] op_sel_hi:[1,0]
	v_mov_b32_e32 v6, v19
	v_pk_mul_f32 v[114:115], v[116:117], v[114:115]
	v_pk_mul_f32 v[116:117], v[50:51], v[16:17] op_sel_hi:[1,0]
	v_pk_mul_f32 v[18:19], v[30:31], v[16:17] op_sel_hi:[1,0]
	v_pk_mul_f32 v[110:111], v[116:117], v[110:111]
	v_pk_mul_f32 v[116:117], v[8:9], v[16:17] op_sel_hi:[1,0]
	v_pk_mul_f32 v[20:21], v[4:5], v[16:17] op_sel_hi:[1,0]
	v_pk_mul_f32 v[106:107], v[0:1], v[16:17] op_sel_hi:[1,0]
	v_pk_mul_f32 v[90:91], v[116:117], v[90:91]
	v_pk_mul_f32 v[116:117], v[48:49], v[16:17] op_sel_hi:[1,0]
	v_pk_mul_f32 v[18:19], v[18:19], v[148:149]
	v_pk_mul_f32 v[20:21], v[20:21], v[24:25]
	v_pk_mul_f32 v[24:25], v[28:29], v[16:17] op_sel_hi:[1,0]
	v_pk_mul_f32 v[92:93], v[6:7], v[16:17] op_sel_hi:[1,0]
	v_pk_mul_f32 v[94:95], v[22:23], v[16:17] op_sel_hi:[1,0]
	v_pk_mul_f32 v[26:27], v[106:107], v[26:27]
	v_pk_mul_f32 v[106:107], v[58:59], v[16:17] op_sel_hi:[1,0]
	v_pk_mul_f32 v[108:109], v[2:3], v[16:17] op_sel_hi:[1,0]
	v_pk_mul_f32 v[116:117], v[116:117], v[60:61]
	v_pk_mul_f32 v[16:17], v[10:11], v[16:17] op_sel_hi:[1,0]
	v_mov_b32_e32 v60, v43
	v_mov_b32_e32 v61, v42
	v_pk_mul_f32 v[104:105], v[16:17], v[104:105]
	v_pk_mul_f32 v[16:17], v[60:61], v[18:19]
	v_pk_mul_f32 v[106:107], v[106:107], v[128:129]
	v_sub_f32_e32 v16, v16, v17
	v_mul_f32_e32 v128, 0x3e38aa3b, v16
	v_pk_mul_f32 v[16:17], v[42:43], v[18:19]
	v_mov_b32_e32 v100, v63
	v_mov_b32_e32 v101, v62
	v_add_f32_e32 v16, v16, v17
	v_pk_mul_f32 v[108:109], v[108:109], v[132:133]
	v_mul_f32_e32 v132, 0x3e38aa3b, v16
	v_pk_mul_f32 v[16:17], v[100:101], v[102:103]
	v_pk_mul_f32 v[24:25], v[24:25], v[140:141]
	v_sub_f32_e32 v16, v16, v17
	v_mul_f32_e32 v100, 0x3e38aa3b, v16
	v_pk_mul_f32 v[16:17], v[62:63], v[102:103]
	v_mov_b32_e32 v62, v45
	v_add_f32_e32 v16, v16, v17
	v_mul_f32_e32 v140, 0x3e38aa3b, v16
	v_pk_mul_f32 v[16:17], v[44:45], v[20:21]
	v_mov_b32_e32 v63, v44
	v_sub_f32_e32 v16, v16, v17
	v_mul_f32_e32 v101, 0x3e38aa3b, v16
	v_pk_mul_f32 v[16:17], v[62:63], v[20:21]
	v_mov_b32_e32 v118, v65
	v_add_f32_e32 v16, v16, v17
	v_mul_f32_e32 v102, 0x3e38aa3b, v16
	v_pk_mul_f32 v[16:17], v[64:65], v[88:89]
	v_mov_b32_e32 v119, v64
	v_sub_f32_e32 v16, v16, v17
	v_mul_f32_e32 v103, 0x3e38aa3b, v16
	v_pk_mul_f32 v[16:17], v[118:119], v[88:89]
	v_mov_b32_e32 v64, v47
	v_add_f32_e32 v16, v16, v17
	v_mov_b32_e32 v65, v46
	v_mul_f32_e32 v118, 0x3e38aa3b, v16
	v_pk_mul_f32 v[16:17], v[64:65], v[24:25]
	v_mul_f32_e32 v32, 0.15915494, v32
	v_sub_f32_e32 v16, v16, v17
	v_mul_f32_e32 v119, 0x3e38aa3b, v16
	v_pk_mul_f32 v[16:17], v[46:47], v[24:25]
	v_mov_b32_e32 v120, v71
	v_mov_b32_e32 v121, v70
	v_add_f32_e32 v16, v16, v17
	v_sin_f32_e32 v33, v32
	v_cos_f32_e32 v32, v32
	v_mul_f32_e32 v133, 0x3e38aa3b, v16
	v_pk_mul_f32 v[16:17], v[120:121], v[112:113]
	v_pk_mul_f32 v[92:93], v[92:93], v[144:145]
	v_sub_f32_e32 v16, v16, v17
	v_mul_f32_e32 v120, 0x3e38aa3b, v16
	v_pk_mul_f32 v[16:17], v[70:71], v[112:113]
	v_mul_f32_e32 v35, 0.15915494, v34
	v_add_f32_e32 v16, v16, v17
	v_mul_f32_e32 v70, 0x3e38aa3b, v16
	v_pk_mul_f32 v[16:17], v[32:33], v[92:93]
	v_sin_f32_e32 v34, v35
	v_sub_f32_e32 v16, v16, v17
	v_mul_f32_e32 v71, 0x3e38aa3b, v16
	v_mov_b32_e32 v16, v33
	v_mov_b32_e32 v17, v32
	v_pk_mul_f32 v[18:19], v[16:17], v[92:93]
	v_cos_f32_e32 v35, v35
	v_add_f32_e32 v18, v18, v19
	v_mul_f32_e32 v112, 0x3e38aa3b, v18
	v_pk_mul_f32 v[18:19], v[72:73], v[114:115]
	v_mov_b32_e32 v122, v73
	v_mov_b32_e32 v123, v72
	v_sub_f32_e32 v18, v18, v19
	v_mul_f32_e32 v72, 0x3e38aa3b, v18
	v_pk_mul_f32 v[18:19], v[122:123], v[114:115]
	v_pk_mul_f32 v[94:95], v[94:95], v[136:137]
	v_add_f32_e32 v18, v18, v19
	v_mul_f32_e32 v73, 0x3e38aa3b, v18
	v_mov_b32_e32 v18, v35
	v_mov_b32_e32 v19, v34
	v_pk_mul_f32 v[20:21], v[18:19], v[94:95]
	v_mul_f32_e32 v36, 0.15915494, v36
	v_sub_f32_e32 v20, v20, v21
	v_mul_f32_e32 v113, 0x3e38aa3b, v20
	v_pk_mul_f32 v[20:21], v[34:35], v[94:95]
	v_mov_b32_e32 v124, v75
	v_mov_b32_e32 v125, v74
	v_add_f32_e32 v20, v20, v21
	v_sin_f32_e32 v37, v36
	v_cos_f32_e32 v36, v36
	v_mul_f32_e32 v114, 0x3e38aa3b, v20
	v_pk_mul_f32 v[20:21], v[124:125], v[110:111]
	v_mul_f32_e32 v39, 0.15915494, v38
	v_sub_f32_e32 v20, v20, v21
	v_mul_f32_e32 v115, 0x3e38aa3b, v20
	v_pk_mul_f32 v[20:21], v[74:75], v[110:111]
	v_sin_f32_e32 v38, v39
	v_add_f32_e32 v20, v20, v21
	v_mul_f32_e32 v74, 0x3e38aa3b, v20
	v_pk_mul_f32 v[20:21], v[36:37], v[26:27]
	v_cos_f32_e32 v39, v39
	v_sub_f32_e32 v20, v20, v21
	v_mul_f32_e32 v75, 0x3e38aa3b, v20
	v_mov_b32_e32 v20, v37
	v_mov_b32_e32 v21, v36
	v_pk_mul_f32 v[24:25], v[20:21], v[26:27]
	v_mov_b32_e32 v126, v77
	v_add_f32_e32 v24, v24, v25
	v_mul_f32_e32 v110, 0x3e38aa3b, v24
	v_pk_mul_f32 v[24:25], v[76:77], v[90:91]
	v_mov_b32_e32 v127, v76
	v_sub_f32_e32 v24, v24, v25
	v_mul_f32_e32 v76, 0x3e38aa3b, v24
	v_pk_mul_f32 v[24:25], v[126:127], v[90:91]
	v_mov_b32_e32 v78, v67
	v_add_f32_e32 v24, v24, v25
	v_or_b32_e32 v25, 32, v80
	v_or_b32_e32 v25, s71, v25
	v_mad_i64_i32 v[56:57], s[52:53], v25, s25, v[56:57]
	v_mul_f32_e32 v77, 0x3e38aa3b, v24
	v_mov_b32_e32 v24, v39
	v_mov_b32_e32 v25, v38
	v_pk_mul_f32 v[26:27], v[24:25], v[106:107]
	v_mov_b32_e32 v79, v66
	v_sub_f32_e32 v26, v26, v27
	v_mul_f32_e32 v111, 0x3e38aa3b, v26
	v_pk_mul_f32 v[26:27], v[38:39], v[106:107]
	global_load_dwordx4 v[88:91], v[56:57], off offset:64
	global_load_dwordx4 v[92:95], v[56:57], off offset:96
	v_add_f32_e32 v26, v26, v27
	v_mul_f32_e32 v106, 0x3e38aa3b, v26
	v_pk_mul_f32 v[26:27], v[78:79], v[116:117]
	v_cvt_pk_bf16_f32 v128, v128, v101
	v_cvt_pk_bf16_f32 v132, v132, v102
	v_cvt_pk_bf16_f32 v136, v100, v103
	v_cvt_pk_bf16_f32 v130, v113, v75
	v_cvt_pk_bf16_f32 v142, v74, v77
	s_nop 0
	v_sub_f32_e32 v26, v26, v27
	v_mul_f32_e32 v78, 0x3e38aa3b, v26
	v_pk_mul_f32 v[26:27], v[66:67], v[116:117]
	v_cvt_pk_bf16_f32 v137, v120, v72
	v_cvt_pk_bf16_f32 v141, v70, v73
	v_cvt_pk_bf16_f32 v129, v119, v71
	v_cvt_pk_bf16_f32 v138, v115, v76
	v_cvt_pk_bf16_f32 v134, v114, v110
	s_nop 0
	v_add_f32_e32 v26, v26, v27
	v_mul_f32_e32 v79, 0x3e38aa3b, v26
	v_pk_mul_f32 v[26:27], v[40:41], v[108:109]
	v_cvt_pk_bf16_f32 v140, v140, v118
	v_cvt_pk_bf16_f32 v133, v133, v112
	v_and_b32_e32 v98, 63, v96
	v_sub_f32_e32 v26, v26, v27
	v_mul_f32_e32 v107, 0x3e38aa3b, v26
	v_mov_b32_e32 v26, v41
	v_mov_b32_e32 v27, v40
	v_pk_mul_f32 v[66:67], v[26:27], v[108:109]
	v_cvt_pk_bf16_f32 v131, v111, v107
	s_ashr_i32 s1, s0, 31
	v_add_f32_e32 v66, v66, v67
	v_mul_f32_e32 v108, 0x3e38aa3b, v66
	v_pk_mul_f32 v[66:67], v[68:69], v[104:105]
	v_cvt_pk_bf16_f32 v135, v106, v108
	s_lshl_b64 s[0:1], s[0:1], 2
	v_sub_f32_e32 v66, v66, v67
	v_mul_f32_e32 v109, 0x3e38aa3b, v66
	v_mov_b32_e32 v66, v69
	v_mov_b32_e32 v67, v68
	v_pk_mul_f32 v[66:67], v[66:67], v[104:105]
	global_load_dwordx4 v[100:103], v[56:57], off
	global_load_dwordx4 v[104:107], v[56:57], off offset:32
	v_bitop3_b32 v56, v80, 63, 32 bitop3:0xc8
	v_cvt_f32_ubyte0_e32 v56, v56
	v_mul_f32_e32 v57, v81, v56
	v_mul_f32_e32 v57, 0.15915494, v57
	v_sin_f32_e32 v80, v57
	v_cos_f32_e32 v81, v57
	v_mul_f32_e32 v57, v82, v56
	v_mul_f32_e32 v57, 0.15915494, v57
	v_cvt_pk_bf16_f32 v139, v78, v109
	v_sin_f32_e32 v109, v57
	v_cos_f32_e32 v108, v57
	v_mul_f32_e32 v57, v83, v56
	v_mul_f32_e32 v57, 0.15915494, v57
	v_sin_f32_e32 v74, v57
	v_cos_f32_e32 v75, v57
	v_mul_f32_e32 v57, v84, v56
	v_mul_f32_e32 v57, 0.15915494, v57
	v_sin_f32_e32 v73, v57
	v_cos_f32_e32 v72, v57
	v_mul_f32_e32 v57, v85, v56
	v_mul_f32_e32 v57, 0.15915494, v57
	v_sin_f32_e32 v70, v57
	v_cos_f32_e32 v71, v57
	v_mul_f32_e32 v57, v86, v56
	v_mul_f32_e32 v57, 0.15915494, v57
	v_sin_f32_e32 v69, v57
	v_cos_f32_e32 v68, v57
	v_mul_f32_e32 v57, v87, v56
	v_mul_f32_e32 v56, v99, v56
	v_mov_b32_e32 v122, v81
	v_mov_b32_e32 v123, v80
	v_mov_b32_e32 v124, v109
	v_mov_b32_e32 v125, v108
	v_add_f32_e32 v66, v66, v67
	v_mul_f32_e32 v66, 0x3e38aa3b, v66
	v_cvt_pk_bf16_f32 v143, v79, v66
	v_mov_b32_e32 v78, v75
	v_mov_b32_e32 v79, v74
	s_waitcnt vmcnt(3)
	v_lshlrev_b32_e32 v82, 16, v91
	v_and_b32_e32 v84, 0xffff0000, v91
	s_waitcnt vmcnt(2)
	v_lshlrev_b32_e32 v83, 16, v95
	v_and_b32_e32 v85, 0xffff0000, v95
	v_mov_b32_e32 v76, v84
	v_mov_b32_e32 v77, v82
	v_pk_mul_f32 v[86:87], v[76:77], v[76:77]
	v_mov_b32_e32 v76, v85
	v_mov_b32_e32 v77, v83
	v_lshlrev_b32_e32 v113, 16, v94
	v_and_b32_e32 v91, 0xffff0000, v94
	v_pk_mul_f32 v[110:111], v[76:77], v[76:77]
	v_mov_b32_e32 v76, v91
	v_mov_b32_e32 v77, v113
	v_lshlrev_b32_e32 v115, 16, v93
	v_and_b32_e32 v117, 0xffff0000, v93
	v_pk_mul_f32 v[94:95], v[76:77], v[76:77]
	v_lshlrev_b32_e32 v114, 16, v89
	v_and_b32_e32 v116, 0xffff0000, v89
	v_mov_b32_e32 v76, v117
	v_mov_b32_e32 v77, v115
	v_lshlrev_b32_e32 v121, 16, v92
	v_and_b32_e32 v89, 0xffff0000, v92
	v_pk_mul_f32 v[118:119], v[76:77], v[76:77]
	v_mov_b32_e32 v76, v89
	v_mov_b32_e32 v77, v121
	v_pk_mul_f32 v[92:93], v[76:77], v[76:77]
	v_lshlrev_b32_e32 v120, 16, v88
	v_and_b32_e32 v88, 0xffff0000, v88
	v_lshlrev_b32_e32 v112, 16, v90
	v_and_b32_e32 v90, 0xffff0000, v90
	v_mov_b32_e32 v76, v73
	v_mul_f32_e32 v57, 0.15915494, v57
	v_sin_f32_e32 v66, v57
	v_cos_f32_e32 v67, v57
	s_add_u32 s0, s18, s0
	s_addc_u32 s1, s19, s1
	v_mul_f32_e32 v56, 0.15915494, v56
	v_sin_f32_e32 v57, v56
	v_cos_f32_e32 v56, v56
	s_waitcnt vmcnt(1)
	v_lshlrev_b32_e32 v154, 16, v101
	v_and_b32_e32 v158, 0xffff0000, v101
	s_waitcnt vmcnt(0)
	v_lshlrev_b32_e32 v163, 16, v104
	v_lshlrev_b32_e32 v162, 16, v100
	v_and_b32_e32 v101, 0xffff0000, v104
	v_and_b32_e32 v100, 0xffff0000, v100
	v_lshlrev_b32_e32 v155, 16, v105
	v_and_b32_e32 v159, 0xffff0000, v105
	v_pk_mul_f32 v[164:165], v[162:163], v[162:163]
	v_pk_mul_f32 v[104:105], v[100:101], v[100:101]
	v_pk_mul_f32 v[156:157], v[154:155], v[154:155]
	v_add_f32_e32 v77, v164, v104
	v_lshlrev_b32_e32 v151, 16, v106
	v_lshlrev_b32_e32 v150, 16, v102
	v_pk_mul_f32 v[160:161], v[158:159], v[158:159]
	v_add_f32_e32 v77, v156, v77
	v_lshlrev_b32_e32 v126, 16, v103
	v_and_b32_e32 v146, 0xffff0000, v103
	v_pk_mul_f32 v[152:153], v[150:151], v[150:151]
	v_and_b32_e32 v103, 0xffff0000, v106
	v_and_b32_e32 v102, 0xffff0000, v102
	v_add_f32_e32 v77, v160, v77
	v_lshlrev_b32_e32 v127, 16, v107
	v_and_b32_e32 v147, 0xffff0000, v107
	v_pk_mul_f32 v[106:107], v[102:103], v[102:103]
	v_add_f32_e32 v77, v152, v77
	v_pk_mul_f32 v[144:145], v[126:127], v[126:127]
	v_add_f32_e32 v77, v106, v77
	v_pk_mul_f32 v[148:149], v[146:147], v[146:147]
	v_add_f32_e32 v77, v144, v77
	v_add_f32_e32 v77, v148, v77
	v_add_f32_e32 v77, v165, v77
	v_add_f32_e32 v77, v105, v77
	v_add_f32_e32 v77, v157, v77
	v_add_f32_e32 v77, v161, v77
	v_add_f32_e32 v77, v153, v77
	v_add_f32_e32 v77, v107, v77
	v_add_f32_e32 v77, v145, v77
	v_add_f32_e32 v77, v149, v77
	v_fmac_f32_e32 v77, v120, v120
	v_fmac_f32_e32 v77, v88, v88
	v_fmac_f32_e32 v77, v114, v114
	v_fmac_f32_e32 v77, v116, v116
	v_fmac_f32_e32 v77, v112, v112
	v_fmac_f32_e32 v77, v90, v90
	v_add_f32_e32 v77, v87, v77
	v_add_f32_e32 v77, v86, v77
	v_add_f32_e32 v77, v93, v77
	v_add_f32_e32 v77, v92, v77
	v_add_f32_e32 v77, v119, v77
	v_add_f32_e32 v77, v118, v77
	v_add_f32_e32 v77, v95, v77
	v_add_f32_e32 v77, v94, v77
	v_add_f32_e32 v77, v111, v77
	v_add_f32_e32 v93, v110, v77
	ds_bpermute_b32 v94, v221, v93
	v_mov_b32_e32 v77, v72
	v_mov_b32_e32 v86, v71
	v_mov_b32_e32 v87, v70
	v_mov_b32_e32 v92, v69
	s_waitcnt lgkmcnt(0)
	v_add_f32_e32 v93, v93, v94
	v_fmamk_f32 v93, v93, 0x3c800000, v211
	v_mul_f32_e32 v94, 0x4b800000, v93
	v_cmp_gt_f32_e32 vcc, s33, v93
	v_mov_b32_e32 v95, v66
	s_lshl_b32 s52, s4, 8
	v_cndmask_b32_e32 v93, v93, v94, vcc
	v_rsq_f32_e32 v99, v93
	v_mov_b32_e32 v93, v68
	v_mov_b32_e32 v94, v67
	s_ashr_i32 s53, s52, 31
	v_mul_f32_e32 v104, 0x45800000, v99
	v_cndmask_b32_e32 v104, v99, v104, vcc
	v_pk_mul_f32 v[30:31], v[30:31], v[104:105] op_sel_hi:[1,0]
	v_pk_mul_f32 v[54:55], v[54:55], v[104:105] op_sel_hi:[1,0]
	v_pk_mul_f32 v[30:31], v[30:31], v[162:163]
	v_pk_mul_f32 v[54:55], v[54:55], v[120:121]
	v_pk_mul_f32 v[60:61], v[60:61], v[30:31]
	v_pk_mul_f32 v[30:31], v[42:43], v[30:31]
	v_pk_mul_f32 v[4:5], v[4:5], v[104:105] op_sel_hi:[1,0]
	v_add_f32_e32 v30, v30, v31
	v_mul_f32_e32 v42, 0x3e38aa3b, v30
	v_pk_mul_f32 v[30:31], v[122:123], v[54:55]
	v_pk_mul_f32 v[4:5], v[4:5], v[100:101]
	v_sub_f32_e32 v30, v30, v31
	v_mul_f32_e32 v43, 0x3e38aa3b, v30
	v_pk_mul_f32 v[30:31], v[80:81], v[54:55]
	v_pk_mul_f32 v[12:13], v[12:13], v[104:105] op_sel_hi:[1,0]
	v_add_f32_e32 v30, v30, v31
	v_mul_f32_e32 v54, 0x3e38aa3b, v30
	v_pk_mul_f32 v[30:31], v[44:45], v[4:5]
	v_pk_mul_f32 v[4:5], v[62:63], v[4:5]
	v_pk_mul_f32 v[12:13], v[12:13], v[88:89]
	v_add_f32_e32 v4, v4, v5
	v_sub_f32_e32 v30, v30, v31
	v_mul_f32_e32 v31, 0x3e38aa3b, v4
	v_pk_mul_f32 v[4:5], v[108:109], v[12:13]
	v_pk_mul_f32 v[28:29], v[28:29], v[104:105] op_sel_hi:[1,0]
	v_sub_f32_e32 v4, v4, v5
	v_mul_f32_e32 v44, 0x3e38aa3b, v4
	v_pk_mul_f32 v[4:5], v[124:125], v[12:13]
	v_pk_mul_f32 v[28:29], v[28:29], v[154:155]
	v_add_f32_e32 v4, v4, v5
	v_mul_f32_e32 v12, 0x3e38aa3b, v4
	v_pk_mul_f32 v[4:5], v[64:65], v[28:29]
	v_pk_mul_f32 v[52:53], v[52:53], v[104:105] op_sel_hi:[1,0]
	v_sub_f32_e32 v4, v4, v5
	v_mul_f32_e32 v13, 0x3e38aa3b, v4
	v_pk_mul_f32 v[4:5], v[46:47], v[28:29]
	v_lshlrev_b32_e32 v28, 2, v98
	global_load_dword v29, v28, s[14:15]
	v_pk_mul_f32 v[52:53], v[52:53], v[114:115]
	global_load_dword v28, v28, s[16:17]
	v_add_f32_e32 v4, v4, v5
	v_mul_f32_e32 v45, 0x3e38aa3b, v4
	v_pk_mul_f32 v[4:5], v[78:79], v[52:53]
	v_pk_mul_f32 v[6:7], v[6:7], v[104:105] op_sel_hi:[1,0]
	v_sub_f32_e32 v4, v4, v5
	v_mul_f32_e32 v46, 0x3e38aa3b, v4
	v_pk_mul_f32 v[4:5], v[74:75], v[52:53]
	v_pk_mul_f32 v[6:7], v[6:7], v[158:159]
	v_add_f32_e32 v4, v4, v5
	v_mul_f32_e32 v47, 0x3e38aa3b, v4
	v_pk_mul_f32 v[4:5], v[32:33], v[6:7]
	v_pk_mul_f32 v[14:15], v[14:15], v[104:105] op_sel_hi:[1,0]
	v_sub_f32_e32 v4, v4, v5
	v_mul_f32_e32 v32, 0x3e38aa3b, v4
	v_pk_mul_f32 v[4:5], v[16:17], v[6:7]
	v_pk_mul_f32 v[14:15], v[14:15], v[116:117]
	v_add_f32_e32 v4, v4, v5
	v_mul_f32_e32 v6, 0x3e38aa3b, v4
	v_pk_mul_f32 v[4:5], v[72:73], v[14:15]
	v_pk_mul_f32 v[22:23], v[22:23], v[104:105] op_sel_hi:[1,0]
	v_sub_f32_e32 v4, v4, v5
	v_mul_f32_e32 v7, 0x3e38aa3b, v4
	v_pk_mul_f32 v[4:5], v[76:77], v[14:15]
	v_pk_mul_f32 v[22:23], v[22:23], v[150:151]
	v_add_f32_e32 v4, v4, v5
	v_mul_f32_e32 v14, 0x3e38aa3b, v4
	v_pk_mul_f32 v[4:5], v[18:19], v[22:23]
	v_pk_mul_f32 v[50:51], v[50:51], v[104:105] op_sel_hi:[1,0]
	v_sub_f32_e32 v4, v4, v5
	v_mul_f32_e32 v15, 0x3e38aa3b, v4
	v_pk_mul_f32 v[4:5], v[34:35], v[22:23]
	v_pk_mul_f32 v[50:51], v[50:51], v[112:113]
	v_add_f32_e32 v4, v4, v5
	v_mul_f32_e32 v16, 0x3e38aa3b, v4
	v_pk_mul_f32 v[4:5], v[86:87], v[50:51]
	v_pk_mul_f32 v[0:1], v[0:1], v[104:105] op_sel_hi:[1,0]
	v_sub_f32_e32 v4, v4, v5
	v_mul_f32_e32 v17, 0x3e38aa3b, v4
	v_pk_mul_f32 v[4:5], v[70:71], v[50:51]
	v_pk_mul_f32 v[0:1], v[0:1], v[102:103]
	v_add_f32_e32 v4, v4, v5
	v_pk_mul_f32 v[8:9], v[8:9], v[104:105] op_sel_hi:[1,0]
	v_mul_f32_e32 v18, 0x3e38aa3b, v4
	v_pk_mul_f32 v[4:5], v[36:37], v[0:1]
	v_pk_mul_f32 v[0:1], v[20:21], v[0:1]
	v_pk_mul_f32 v[8:9], v[8:9], v[90:91]
	v_add_f32_e32 v0, v0, v1
	v_sub_f32_e32 v4, v4, v5
	v_mul_f32_e32 v5, 0x3e38aa3b, v0
	v_pk_mul_f32 v[0:1], v[68:69], v[8:9]
	v_pk_mul_f32 v[58:59], v[58:59], v[104:105] op_sel_hi:[1,0]
	v_sub_f32_e32 v0, v0, v1
	v_mul_f32_e32 v19, 0x3e38aa3b, v0
	v_pk_mul_f32 v[0:1], v[92:93], v[8:9]
	v_pk_mul_f32 v[58:59], v[58:59], v[126:127]
	v_add_f32_e32 v0, v0, v1
	v_mul_f32_e32 v8, 0x3e38aa3b, v0
	v_pk_mul_f32 v[0:1], v[24:25], v[58:59]
	v_pk_mul_f32 v[48:49], v[48:49], v[104:105] op_sel_hi:[1,0]
	v_sub_f32_e32 v0, v0, v1
	v_mul_f32_e32 v9, 0x3e38aa3b, v0
	v_pk_mul_f32 v[0:1], v[38:39], v[58:59]
	v_pk_mul_f32 v[48:49], v[48:49], v[82:83]
	v_add_f32_e32 v0, v0, v1
	v_mul_f32_e32 v20, 0x3e38aa3b, v0
	v_pk_mul_f32 v[0:1], v[94:95], v[48:49]
	v_pk_mul_f32 v[2:3], v[2:3], v[104:105] op_sel_hi:[1,0]
	v_sub_f32_e32 v0, v0, v1
	v_mul_f32_e32 v21, 0x3e38aa3b, v0
	v_pk_mul_f32 v[0:1], v[66:67], v[48:49]
	v_pk_mul_f32 v[2:3], v[2:3], v[146:147]
	v_add_f32_e32 v0, v0, v1
	v_mul_f32_e32 v22, 0x3e38aa3b, v0
	v_pk_mul_f32 v[0:1], v[40:41], v[2:3]
	v_pk_mul_f32 v[10:11], v[10:11], v[104:105] op_sel_hi:[1,0]
	v_sub_f32_e32 v0, v0, v1
	v_mul_f32_e32 v23, 0x3e38aa3b, v0
	v_pk_mul_f32 v[0:1], v[26:27], v[2:3]
	global_load_dword v2, v199, s[0:1]
	v_pk_mul_f32 v[10:11], v[10:11], v[84:85]
	v_add_f32_e32 v0, v0, v1
	v_mul_f32_e32 v3, 0x3e38aa3b, v0
	v_pk_mul_f32 v[0:1], v[56:57], v[10:11]
	v_cmp_lt_i32_e32 vcc, v215, v209
	v_sub_f32_e32 v0, v0, v1
	v_mul_f32_e32 v24, 0x3e38aa3b, v0
	v_mov_b32_e32 v0, v57
	v_mov_b32_e32 v1, v56
	v_pk_mul_f32 v[0:1], v[0:1], v[10:11]
	v_mul_f32_e32 v4, 0x3e38aa3b, v4
	v_add_f32_e32 v0, v0, v1
	v_cndmask_b32_e32 v1, v207, v215, vcc
	v_mul_f32_e32 v10, 0x3e38aa3b, v0
	s_waitcnt vmcnt(2)
	v_and_b32_e32 v0, 0x7fffffff, v29
	v_lshlrev_b32_e32 v223, 2, v1
	ds_bpermute_b32 v0, v223, v0
	s_waitcnt vmcnt(1)
	v_and_b32_e32 v1, 0x7fffffff, v28
	ds_bpermute_b32 v1, v223, v1
	v_cmp_lt_i32_e32 vcc, v216, v209
	v_cvt_pk_bf16_f32 v146, v15, v4
	v_cvt_pk_bf16_f32 v147, v9, v23
	s_waitcnt lgkmcnt(1)
	v_max_f32_e32 v0, v0, v0
	v_max_f32_e64 v4, |v29|, |v29|
	v_cndmask_b32_e32 v9, v207, v216, vcc
	v_max_f32_e32 v0, v4, v0
	v_lshlrev_b32_e32 v224, 2, v9
	s_waitcnt lgkmcnt(0)
	v_max_f32_e32 v1, v1, v1
	v_max_f32_e64 v4, |v28|, |v28|
	ds_bpermute_b32 v9, v224, v0
	v_max_f32_e32 v1, v4, v1
	ds_bpermute_b32 v4, v224, v1
	v_cvt_pk_bf16_f32 v150, v16, v5
	v_cmp_lt_i32_e32 vcc, v217, v209
	s_waitcnt lgkmcnt(1)
	v_max_f32_e32 v5, v9, v9
	v_max_f32_e32 v0, v0, v5
	v_cndmask_b32_e32 v5, v207, v217, vcc
	s_waitcnt lgkmcnt(0)
	v_max_f32_e32 v4, v4, v4
	v_lshlrev_b32_e32 v5, 2, v5
	v_cvt_pk_bf16_f32 v149, v45, v6
	ds_bpermute_b32 v6, v5, v0
	v_max_f32_e32 v1, v1, v4
	ds_bpermute_b32 v4, v5, v1
	v_cvt_pk_bf16_f32 v151, v20, v3
	v_cmp_lt_i32_e32 vcc, v218, v209
	s_waitcnt lgkmcnt(1)
	v_max_f32_e32 v3, v6, v6
	v_max_f32_e32 v0, v0, v3
	s_waitcnt lgkmcnt(0)
	v_max_f32_e32 v3, v4, v4
	v_cndmask_b32_e32 v4, v207, v218, vcc
	v_lshlrev_b32_e32 v4, 2, v4
	ds_bpermute_b32 v5, v4, v0
	v_max_f32_e32 v1, v1, v3
	ds_bpermute_b32 v3, v4, v1
	v_cmp_lt_i32_e32 vcc, v219, v209
	s_mov_b32 s0, 0x3fb8aa3b
	s_waitcnt lgkmcnt(1)
	v_max_f32_e32 v4, v5, v5
	v_max_f32_e32 v0, v0, v4
	v_cndmask_b32_e32 v4, v207, v219, vcc
	s_waitcnt lgkmcnt(0)
	v_max_f32_e32 v3, v3, v3
	v_lshlrev_b32_e32 v4, 2, v4
	ds_bpermute_b32 v5, v4, v0
	v_max_f32_e32 v1, v1, v3
	ds_bpermute_b32 v3, v4, v1
	v_ashrrev_i32_e32 v200, 2, v96
	v_ashrrev_i32_e32 v201, 31, v200
	s_waitcnt lgkmcnt(1)
	v_max_f32_e32 v4, v5, v5
	v_max_f32_e32 v0, v0, v4
	s_waitcnt lgkmcnt(0)
	v_max_f32_e32 v3, v3, v3
	ds_bpermute_b32 v4, v221, v0
	v_max_f32_e32 v1, v1, v3
	ds_bpermute_b32 v3, v221, v1
	v_bfe_u32 v225, v96, 1, 1
	v_and_b32_e32 v226, 1, v96
	s_waitcnt lgkmcnt(1)
	v_max_f32_e32 v4, v4, v4
	v_max_f32_e32 v0, v0, v4
	s_waitcnt lgkmcnt(0)
	v_max_f32_e32 v3, v3, v3
	v_max_f32_e32 v1, v1, v3
	v_mul_f32_e32 v0, 0x41000000, v0
	v_mul_f32_e32 v0, v1, v0
	v_mul_f32_e32 v0, 0x3fb8aa3b, v0
	s_waitcnt vmcnt(0)
	v_mul_f32_e32 v235, 0x3fb8aa3b, v2
	v_fmamk_f32 v0, v0, 0x3f828f5c, v212
	v_max_f32_e32 v4, v0, v235
	v_fma_f32 v5, v2, s0, -v4
	s_add_u32 s0, s52, 0x10000
	s_addc_u32 s1, s53, 0
	v_lshl_add_u64 v[0:1], s[0:1], 0, v[200:201]
	v_mov_b64_e32 v[2:3], s[28:29]
	v_mad_u64_u32 v[2:3], s[0:1], v0, s25, v[2:3]
	v_mad_i32_i24 v3, v1, s25, v3
	s_lshl_b32 s8, s2, 7
	v_lshl_add_u64 v[0:1], v[2:3], 0, s[8:9]
	v_lshlrev_b32_e32 v198, 6, v225
	v_and_b32_e32 v6, 3, v96
	v_lshl_add_u64 v[2:3], v[0:1], 0, v[198:199]
	v_lshlrev_b32_e32 v198, 4, v226
	v_lshl_add_u64 v[2:3], v[2:3], 0, v[198:199]
	v_lshlrev_b32_e32 v198, 5, v6
	v_lshl_add_u64 v[0:1], v[0:1], 0, v[198:199]
	v_mov_b64_e32 v[88:89], v[176:177]
	v_mov_b64_e32 v[90:91], v[178:179]
	v_mov_b64_e32 v[92:93], v[180:181]
	v_mov_b64_e32 v[94:95], v[182:183]
	v_mov_b64_e32 v[80:81], v[184:185]
	v_mov_b64_e32 v[82:83], v[186:187]
	v_mov_b64_e32 v[84:85], v[188:189]
	v_mov_b64_e32 v[86:87], v[190:191]
	v_exp_f32_e32 v0, v5
	v_cmp_gt_f32_e32 vcc, s31, v4
	v_cmp_gt_u32_e64 s[0:1], 32, v98
	s_ashr_i32 s5, s4, 31
	v_cndmask_b32_e32 v0, 1.0, v0, vcc
	s_lshl_b32 s85, s7, 1
	v_cndmask_b32_e64 v227, 0, v0, s[0:1]
	s_add_i32 s84, s72, -2
	s_lshl_b64 s[0:1], s[4:5], 12
	s_or_b32 s86, s85, 1
	v_lshlrev_b32_e32 v1, 4, v96
	v_lshl_add_u32 v0, v225, 13, 0
	s_add_u32 s52, s52, 0x10080
	v_and_b32_e32 v1, 0xc0, v1
	v_lshlrev_b32_e32 v2, 1, v96
	v_sub_f32_e32 v60, v60, v61
	v_mul_f32_e32 v30, 0x3e38aa3b, v30
	v_cvt_pk_bf16_f32 v154, v17, v19
	v_cvt_pk_bf16_f32 v155, v21, v24
	v_cvt_pk_bf16_f32 v157, v47, v14
	v_cvt_pk_bf16_f32 v158, v18, v8
	v_cvt_pk_bf16_f32 v159, v22, v10
	v_lshlrev_b32_e32 v16, 5, v225
	v_lshlrev_b32_e32 v18, 3, v226
	v_lshlrev_b32_e32 v20, 4, v6
	v_lshl_add_u32 v17, v226, 11, v0
	v_lshlrev_b32_e32 v19, 4, v200
	v_lshl_add_u32 v21, v200, 6, v0
	v_lshlrev_b32_e32 v22, 5, v226
	v_lshlrev_b32_e32 v0, 4, v222
	s_addc_u32 s53, s53, 0
	v_lshl_or_b32 v1, v97, 8, v1
	v_and_b32_e32 v2, 32, v2
	v_lshlrev_b32_e32 v3, 3, v6
	v_mov_b32_e32 v14, v199
	v_mov_b32_e32 v15, v199
	v_mul_f32_e32 v60, 0x3e38aa3b, v60
	v_cvt_pk_bf16_f32 v144, v60, v30
	v_cvt_pk_bf16_f32 v145, v13, v32
	v_cvt_pk_bf16_f32 v148, v42, v31
	v_cvt_pk_bf16_f32 v152, v43, v44
	v_cvt_pk_bf16_f32 v153, v46, v7
	v_cvt_pk_bf16_f32 v156, v54, v12
	v_cmp_ngt_f32_e64 s[2:3], s31, v4
	v_cndmask_b32_e64 v48, 0, -v4, vcc
	v_cmp_gt_u32_e64 s[4:5], 2, v6
	v_or_b32_e32 v229, s6, v222
	s_add_u32 s54, s28, s8
	v_or3_b32 v231, v1, v2, v3
	v_lshl_or_b32 v232, v97, 11, v0
	v_mov_b32_e32 v0, v199
	v_mov_b32_e32 v1, v199
	v_mov_b32_e32 v2, v199
	v_mov_b32_e32 v3, v199
	v_mov_b32_e32 v4, v199
	v_mov_b32_e32 v5, v199
	v_mov_b32_e32 v6, v199
	v_mov_b32_e32 v7, v199
	v_mov_b32_e32 v8, v199
	v_mov_b32_e32 v9, v199
	v_mov_b32_e32 v10, v199
	v_mov_b32_e32 v11, v199
	v_mov_b32_e32 v12, v199
	v_mov_b32_e32 v13, v199
	v_lshlrev_b32_e32 v198, 1, v16
	v_lshlrev_b32_e32 v202, 1, v18
	v_lshlrev_b32_e32 v204, 1, v20
	v_add_u32_e32 v233, v17, v19
	v_add_u32_e32 v234, v21, v22
	v_mov_b64_e32 v[30:31], v[14:15]
	v_mov_b64_e32 v[46:47], v[14:15]
	v_mov_b64_e32 v[78:79], v[14:15]
	s_mov_b32 s73, 0
	v_lshlrev_b32_e32 v228, 2, v97
	v_mov_b32_e32 v49, v48
	v_mov_b32_e32 v50, v48
	v_mov_b32_e32 v51, v48
	v_mov_b32_e32 v52, v48
	v_mov_b32_e32 v53, v48
	v_mov_b32_e32 v54, v48
	v_mov_b32_e32 v55, v48
	v_mov_b32_e32 v56, v48
	v_mov_b32_e32 v57, v48
	v_mov_b32_e32 v58, v48
	v_mov_b32_e32 v59, v48
	v_mov_b32_e32 v60, v48
	v_mov_b32_e32 v61, v48
	v_mov_b32_e32 v62, v48
	v_mov_b32_e32 v63, v48
	v_or_b32_e32 v230, 32, v229
	s_addc_u32 s55, s29, 0
	v_mov_b32_e32 v113, v235
	v_mov_b32_e32 v112, v227
	v_mov_b64_e32 v[28:29], v[12:13]
	v_mov_b64_e32 v[26:27], v[10:11]
	v_mov_b64_e32 v[24:25], v[8:9]
	v_mov_b64_e32 v[22:23], v[6:7]
	v_mov_b64_e32 v[20:21], v[4:5]
	v_mov_b64_e32 v[18:19], v[2:3]
	v_mov_b64_e32 v[16:17], v[0:1]
	v_mov_b64_e32 v[44:45], v[12:13]
	v_mov_b64_e32 v[42:43], v[10:11]
	v_mov_b64_e32 v[40:41], v[8:9]
	v_mov_b64_e32 v[38:39], v[6:7]
	v_mov_b64_e32 v[36:37], v[4:5]
	v_mov_b64_e32 v[34:35], v[2:3]
	v_mov_b64_e32 v[32:33], v[0:1]
	v_mov_b64_e32 v[76:77], v[12:13]
	v_mov_b64_e32 v[74:75], v[10:11]
	v_mov_b64_e32 v[72:73], v[8:9]
	v_mov_b64_e32 v[70:71], v[6:7]
	v_mov_b64_e32 v[68:69], v[4:5]
	v_mov_b64_e32 v[66:67], v[2:3]
	v_mov_b64_e32 v[64:65], v[0:1]
	s_mov_b64 s[6:7], -1
	s_cmp_lt_u32 s73, 2
	s_mov_b32 s8, 0
	s_cbranch_scc1 .LBB0_408
